# MLA loop: corrected DMA wait counts (5|3) + per-tile barrier and DMA issue moved to just before the PV MFMAs
# speedup vs baseline: 1.0012x; 1.0012x over previous
.Lmy_nors_3:
	s_waitcnt lgkmcnt(0)
	v_add_u32_e32 v2, 0x6000, v237
	v_mfma_f32_32x32x16_bf16 v[82:97], v[218:221], v[4:7], v[66:81]
	v_exp_f32_e32 v142, v142
	v_exp_f32_e32 v143, v143
	v_exp_f32_e32 v144, v144
	v_add_f32_e32 v27, v142, v143
	v_exp_f32_e32 v145, v145
	ds_read_b64_tr_b16 v[114:115], v2 offset:49152
	ds_read_b64_tr_b16 v[116:117], v2 offset:49664
	ds_read_b64_tr_b16 v[118:119], v2 offset:50176
	ds_read_b64_tr_b16 v[120:121], v2 offset:50688
	v_mfma_f32_32x32x16_bf16 v[98:113], v[214:217], v[4:7], v[66:81]
	v_exp_f32_e32 v146, v146
	v_add_f32_e32 v27, v27, v144
	v_exp_f32_e32 v147, v147
	v_add_f32_e32 v27, v27, v145
	v_exp_f32_e32 v148, v148
	ds_read_b64_tr_b16 v[122:123], v2 offset:51200
	ds_read_b64_tr_b16 v[124:125], v2 offset:51712
	ds_read_b64_tr_b16 v[126:127], v2 offset:52224
	ds_read_b64_tr_b16 v[128:129], v2 offset:52736
	v_mfma_f32_32x32x16_bf16 v[82:97], v[210:213], v[8:11], v[82:97]
	v_add_f32_e32 v27, v27, v146
	v_exp_f32_e32 v149, v149
	v_add_f32_e32 v27, v27, v147
	v_add_f32_e32 v27, v27, v148
	v_add_f32_e32 v27, v27, v149
	ds_read_b64_tr_b16 v[240:241], v2 offset:53248
	ds_read_b64_tr_b16 v[242:243], v2 offset:53760
	ds_read_b64_tr_b16 v[244:245], v2 offset:54272
	ds_read_b64_tr_b16 v[246:247], v2 offset:54784
	v_mfma_f32_32x32x16_bf16 v[98:113], v[206:209], v[8:11], v[98:113]
	v_cvt_pk_bf16_f32 v142, v142, v143
	v_cvt_pk_bf16_f32 v143, v144, v145
	v_cvt_pk_bf16_f32 v144, v146, v147
	v_cvt_pk_bf16_f32 v145, v148, v149
	ds_read_b64_tr_b16 v[248:249], v2 offset:55296
	ds_read_b64_tr_b16 v[250:251], v2 offset:55808
	ds_read_b64_tr_b16 v[20:21], v2 offset:56320
	ds_read_b64_tr_b16 v[22:23], v2 offset:56832
	v_mfma_f32_32x32x16_bf16 v[82:97], v[202:205], v[12:15], v[82:97]
	v_exp_f32_e32 v150, v150
	v_exp_f32_e32 v151, v151
	v_exp_f32_e32 v152, v152
	v_add_f32_e32 v27, v27, v150
	v_exp_f32_e32 v153, v153
	v_mfma_f32_32x32x16_bf16 v[98:113], v[198:201], v[12:15], v[98:113]
	v_add_f32_e32 v27, v27, v151
	v_exp_f32_e32 v154, v154
	v_add_f32_e32 v27, v27, v152
	v_exp_f32_e32 v155, v155
	v_add_f32_e32 v27, v27, v153
	v_mfma_f32_32x32x16_bf16 v[82:97], v[194:197], v[130:133], v[82:97]
	v_exp_f32_e32 v156, v156
	v_add_f32_e32 v27, v27, v154
	v_exp_f32_e32 v157, v157
	v_add_f32_e32 v27, v27, v155
	v_add_f32_e32 v27, v27, v156
	v_mfma_f32_32x32x16_bf16 v[98:113], v[190:193], v[130:133], v[98:113]
	v_add_f32_e32 v27, v27, v157
	v_cvt_pk_bf16_f32 v150, v150, v151
	v_cvt_pk_bf16_f32 v151, v152, v153
	v_cvt_pk_bf16_f32 v152, v154, v155
	v_cvt_pk_bf16_f32 v153, v156, v157
	v_mfma_f32_32x32x16_bf16 v[82:97], v[186:189], v[134:137], v[82:97]
	v_exp_f32_e32 v158, v158
	v_exp_f32_e32 v159, v159
	v_exp_f32_e32 v160, v160
	v_add_f32_e32 v27, v27, v158
	v_exp_f32_e32 v161, v161
	v_mfma_f32_32x32x16_bf16 v[98:113], v[182:185], v[134:137], v[98:113]
	v_add_f32_e32 v27, v27, v159
	v_exp_f32_e32 v162, v162
	v_add_f32_e32 v27, v27, v160
	v_exp_f32_e32 v163, v163
	v_add_f32_e32 v27, v27, v161
	v_mfma_f32_32x32x16_bf16 v[82:97], v[178:181], v[138:141], v[82:97]
	v_exp_f32_e32 v164, v164
	v_add_f32_e32 v27, v27, v162
	v_exp_f32_e32 v165, v165
	v_add_f32_e32 v27, v27, v163
	v_add_f32_e32 v27, v27, v164
	v_mfma_f32_32x32x16_bf16 v[98:113], v[174:177], v[138:141], v[98:113]
	v_add_f32_e32 v27, v27, v165
	v_cvt_pk_bf16_f32 v158, v158, v159
	v_cvt_pk_bf16_f32 v159, v160, v161
	v_cvt_pk_bf16_f32 v160, v162, v163
	v_cvt_pk_bf16_f32 v161, v164, v165
	s_waitcnt vmcnt(5)
	s_barrier
	s_waitcnt lgkmcnt(0)
	v_add_u32_e32 v2, 0x3000, v238
	v_mfma_f32_32x32x16_bf16 v[34:49], v[142:145], v[114:117], v[34:49]
	s_add_u32 m0, s57, 0x4000
	v_exp_f32_e32 v166, v166
	v_exp_f32_e32 v167, v167
	global_load_lds_dwordx4 v[28:29], off
	v_lshl_add_u64 v[28:29], v[28:29], 0, s[30:31]
	v_exp_f32_e32 v168, v168
	v_add_f32_e32 v27, v27, v166
	v_exp_f32_e32 v169, v169
	ds_read_b128 v[218:221], v2
	ds_read_b128 v[214:217], v2 offset:512
	ds_read_b128 v[210:213], v2 offset:2048
	v_mfma_f32_32x32x16_bf16 v[50:65], v[142:145], v[240:243], v[50:65]
	s_cmp_eq_u32 s79, 1
	s_cbranch_scc1 .Lmy_gl_4
	s_add_u32 m0, s40, 0x0
	s_nop 0
	global_load_lds_dwordx4 v[24:25], off
	v_lshl_add_u64 v[24:25], v[24:25], 0, s[30:31]

.Lmy_A_loop:
	s_waitcnt lgkmcnt(0)
	v_mov_b32_e32 v2, v237
	v_mfma_f32_32x32x16_bf16 v[142:157], v[218:221], v[4:7], v[66:81]
	v_exp_f32_e32 v82, v82
	v_exp_f32_e32 v83, v83
	v_exp_f32_e32 v84, v84
	v_add_f32_e32 v27, v82, v83
	v_exp_f32_e32 v85, v85
	ds_read_b64_tr_b16 v[114:115], v2 offset:49152
	ds_read_b64_tr_b16 v[116:117], v2 offset:49664
	ds_read_b64_tr_b16 v[118:119], v2 offset:50176
	ds_read_b64_tr_b16 v[120:121], v2 offset:50688
	v_mfma_f32_32x32x16_bf16 v[158:173], v[214:217], v[4:7], v[66:81]
	v_exp_f32_e32 v86, v86
	v_add_f32_e32 v27, v27, v84
	v_exp_f32_e32 v87, v87
	v_add_f32_e32 v27, v27, v85
	v_exp_f32_e32 v88, v88
	ds_read_b64_tr_b16 v[122:123], v2 offset:51200
	ds_read_b64_tr_b16 v[124:125], v2 offset:51712
	ds_read_b64_tr_b16 v[126:127], v2 offset:52224
	ds_read_b64_tr_b16 v[128:129], v2 offset:52736
	v_mfma_f32_32x32x16_bf16 v[142:157], v[210:213], v[8:11], v[142:157]
	v_add_f32_e32 v27, v27, v86
	v_exp_f32_e32 v89, v89
	v_add_f32_e32 v27, v27, v87
	v_add_f32_e32 v27, v27, v88
	v_add_f32_e32 v27, v27, v89
	ds_read_b64_tr_b16 v[240:241], v2 offset:53248
	ds_read_b64_tr_b16 v[242:243], v2 offset:53760
	ds_read_b64_tr_b16 v[244:245], v2 offset:54272
	ds_read_b64_tr_b16 v[246:247], v2 offset:54784
	v_mfma_f32_32x32x16_bf16 v[158:173], v[206:209], v[8:11], v[158:173]
	v_cvt_pk_bf16_f32 v82, v82, v83
	v_cvt_pk_bf16_f32 v83, v84, v85
	v_cvt_pk_bf16_f32 v84, v86, v87
	v_cvt_pk_bf16_f32 v85, v88, v89
	ds_read_b64_tr_b16 v[248:249], v2 offset:55296
	ds_read_b64_tr_b16 v[250:251], v2 offset:55808
	ds_read_b64_tr_b16 v[20:21], v2 offset:56320
	ds_read_b64_tr_b16 v[22:23], v2 offset:56832
	v_mfma_f32_32x32x16_bf16 v[142:157], v[202:205], v[12:15], v[142:157]
	v_exp_f32_e32 v90, v90
	v_exp_f32_e32 v91, v91
	v_exp_f32_e32 v92, v92
	v_add_f32_e32 v27, v27, v90
	v_exp_f32_e32 v93, v93
	v_mfma_f32_32x32x16_bf16 v[158:173], v[198:201], v[12:15], v[158:173]
	v_add_f32_e32 v27, v27, v91
	v_exp_f32_e32 v94, v94
	v_add_f32_e32 v27, v27, v92
	v_exp_f32_e32 v95, v95
	v_add_f32_e32 v27, v27, v93
	v_mfma_f32_32x32x16_bf16 v[142:157], v[194:197], v[130:133], v[142:157]
	v_exp_f32_e32 v96, v96
	v_add_f32_e32 v27, v27, v94
	v_exp_f32_e32 v97, v97
	v_add_f32_e32 v27, v27, v95
	v_add_f32_e32 v27, v27, v96
	v_mfma_f32_32x32x16_bf16 v[158:173], v[190:193], v[130:133], v[158:173]
	v_add_f32_e32 v27, v27, v97
	v_cvt_pk_bf16_f32 v90, v90, v91
	v_cvt_pk_bf16_f32 v91, v92, v93
	v_cvt_pk_bf16_f32 v92, v94, v95
	v_cvt_pk_bf16_f32 v93, v96, v97
	v_mfma_f32_32x32x16_bf16 v[142:157], v[186:189], v[134:137], v[142:157]
	v_exp_f32_e32 v98, v98
	v_exp_f32_e32 v99, v99
	v_exp_f32_e32 v100, v100
	v_add_f32_e32 v27, v27, v98
	v_exp_f32_e32 v101, v101
	v_mfma_f32_32x32x16_bf16 v[158:173], v[182:185], v[134:137], v[158:173]
	v_add_f32_e32 v27, v27, v99
	v_exp_f32_e32 v102, v102
	v_add_f32_e32 v27, v27, v100
	v_exp_f32_e32 v103, v103
	v_add_f32_e32 v27, v27, v101
	v_mfma_f32_32x32x16_bf16 v[142:157], v[178:181], v[138:141], v[142:157]
	v_exp_f32_e32 v104, v104
	v_add_f32_e32 v27, v27, v102
	v_exp_f32_e32 v105, v105
	v_add_f32_e32 v27, v27, v103
	v_add_f32_e32 v27, v27, v104
	v_mfma_f32_32x32x16_bf16 v[158:173], v[174:177], v[138:141], v[158:173]
	v_add_f32_e32 v27, v27, v105
	v_cvt_pk_bf16_f32 v98, v98, v99
	v_cvt_pk_bf16_f32 v99, v100, v101
	v_cvt_pk_bf16_f32 v100, v102, v103
	v_cvt_pk_bf16_f32 v101, v104, v105
	s_waitcnt vmcnt(5)
	s_barrier
	s_waitcnt lgkmcnt(0)
	v_add_u32_e32 v2, 0x6000, v238
	v_mfma_f32_32x32x16_bf16 v[34:49], v[82:85], v[114:117], v[34:49]
	s_add_u32 m0, s57, 0x6000
	v_exp_f32_e32 v106, v106
	v_exp_f32_e32 v107, v107
	global_load_lds_dwordx4 v[28:29], off
	v_lshl_add_u64 v[28:29], v[28:29], 0, s[30:31]
	v_exp_f32_e32 v108, v108
	v_add_f32_e32 v27, v27, v106
	v_exp_f32_e32 v109, v109
	ds_read_b128 v[218:221], v2
	ds_read_b128 v[214:217], v2 offset:512
	ds_read_b128 v[210:213], v2 offset:2048
	v_mfma_f32_32x32x16_bf16 v[50:65], v[82:85], v[240:243], v[50:65]
	s_add_u32 m0, s40, 0x3000
	v_add_f32_e32 v27, v27, v107
	v_exp_f32_e32 v110, v110
	global_load_lds_dwordx4 v[24:25], off
	v_lshl_add_u64 v[24:25], v[24:25], 0, s[30:31]
	v_add_f32_e32 v27, v27, v108
	v_exp_f32_e32 v111, v111
	v_add_f32_e32 v27, v27, v109
	ds_read_b128 v[206:209], v2 offset:2560
	ds_read_b128 v[202:205], v2 offset:4096
	ds_read_b128 v[198:201], v2 offset:4608
	v_mfma_f32_32x32x16_bf16 v[34:49], v[90:93], v[118:121], v[34:49]
	s_add_u32 m0, s43, 0x3000
	v_exp_f32_e32 v112, v112
	v_add_f32_e32 v27, v27, v110
	global_load_lds_dwordx4 v[30:31], off
	v_lshl_add_u64 v[30:31], v[30:31], 0, s[12:13]
	v_exp_f32_e32 v113, v113
	v_add_f32_e32 v27, v27, v111
	v_add_f32_e32 v27, v27, v112
	ds_read_b128 v[194:197], v2 offset:6144
	ds_read_b128 v[190:193], v2 offset:6656
	ds_read_b128 v[186:189], v2 offset:8192
	v_mfma_f32_32x32x16_bf16 v[50:65], v[90:93], v[244:247], v[50:65]
	v_add_f32_e32 v27, v27, v113
	v_cvt_pk_bf16_f32 v106, v106, v107
	v_cvt_pk_bf16_f32 v107, v108, v109
	v_cvt_pk_bf16_f32 v108, v110, v111
	v_cvt_pk_bf16_f32 v109, v112, v113
	v_add_f32_e32 v236, v236, v27
	ds_read_b128 v[182:185], v2 offset:8704
	ds_read_b128 v[178:181], v2 offset:10240
	ds_read_b128 v[174:177], v2 offset:10752
	v_mfma_f32_32x32x16_bf16 v[34:49], v[98:101], v[122:125], v[34:49]
	v_max3_f32 v19, v142, v143, v144
	v_max3_f32 v26, v145, v146, v147
	v_max3_f32 v19, v19, v148, v149
	v_max3_f32 v26, v26, v150, v151
	v_mfma_f32_32x32x16_bf16 v[50:65], v[98:101], v[248:251], v[50:65]
	v_max3_f32 v19, v19, v152, v153
	v_max3_f32 v26, v26, v154, v155
	v_max3_f32 v19, v19, v156, v157
	v_max3_f32 v26, v26, v158, v159
	v_mfma_f32_32x32x16_bf16 v[34:49], v[106:109], v[126:129], v[34:49]
	v_max3_f32 v19, v19, v160, v161
	v_max3_f32 v26, v26, v162, v163
	v_max3_f32 v19, v19, v164, v165
	v_max3_f32 v26, v26, v166, v167
	v_mfma_f32_32x32x16_bf16 v[50:65], v[106:109], v[20:23], v[50:65]
	v_max3_f32 v19, v19, v168, v169
	v_max3_f32 v26, v26, v170, v171
	v_max3_f32 v19, v19, v172, v173
	v_max_f32_e32 v19, v19, v26
	v_cmp_lt_f32_e32 vcc, s41, v19
	s_cbranch_vccz .Lmy_nors_7
	s_nop 15
	s_nop 15
	v_mov_b32_e32 v26, v19
	s_nop 1
	v_permlane32_swap_b32_e32 v19, v26
	v_max_f32_e32 v19, v19, v26
	v_max_f32_e32 v19, v19, v19
	v_max_f32_e32 v90, 0, v19
	v_exp_f32_e64 v91, -v90
	v_add_f32_e32 v239, v239, v90
	v_xor_b32_e32 v66, 0x80000000, v239
	v_mov_b32_e32 v67, v66
	v_mov_b32_e32 v68, v66
	v_mov_b32_e32 v69, v66
	v_mov_b32_e32 v70, v66
	v_mov_b32_e32 v71, v66
	v_mov_b32_e32 v72, v66
	v_mov_b32_e32 v73, v66
	v_mov_b32_e32 v74, v66
	v_mov_b32_e32 v75, v66
	v_mov_b32_e32 v76, v66
	v_mov_b32_e32 v77, v66
	v_mov_b32_e32 v78, v66
	v_mov_b32_e32 v79, v66
	v_mov_b32_e32 v80, v66
	v_mov_b32_e32 v81, v66
	v_sub_f32_e32 v142, v142, v90
	v_sub_f32_e32 v143, v143, v90
	v_sub_f32_e32 v144, v144, v90
	v_sub_f32_e32 v145, v145, v90
	v_sub_f32_e32 v146, v146, v90
	v_sub_f32_e32 v147, v147, v90
	v_sub_f32_e32 v148, v148, v90
	v_sub_f32_e32 v149, v149, v90
	v_sub_f32_e32 v150, v150, v90
	v_sub_f32_e32 v151, v151, v90
	v_sub_f32_e32 v152, v152, v90
	v_sub_f32_e32 v153, v153, v90
	v_sub_f32_e32 v154, v154, v90
	v_sub_f32_e32 v155, v155, v90
	v_sub_f32_e32 v156, v156, v90
	v_sub_f32_e32 v157, v157, v90
	v_sub_f32_e32 v158, v158, v90
	v_sub_f32_e32 v159, v159, v90
	v_sub_f32_e32 v160, v160, v90
	v_sub_f32_e32 v161, v161, v90
	v_sub_f32_e32 v162, v162, v90
	v_sub_f32_e32 v163, v163, v90
	v_sub_f32_e32 v164, v164, v90
	v_sub_f32_e32 v165, v165, v90
	v_sub_f32_e32 v166, v166, v90
	v_sub_f32_e32 v167, v167, v90
	v_sub_f32_e32 v168, v168, v90
	v_sub_f32_e32 v169, v169, v90
	v_sub_f32_e32 v170, v170, v90
	v_sub_f32_e32 v171, v171, v90
	v_sub_f32_e32 v172, v172, v90
	v_sub_f32_e32 v173, v173, v90
	v_mul_f32_e32 v236, v236, v91
	s_mov_b64 s[96:97], exec
	s_and_b64 exec, exec, s[8:9]
	ds_write_b32 v235, v91
	s_mov_b64 exec, s[96:97]
	v_lshl_add_u32 v2, v228, 4, s47
	ds_read_b128 v[94:97], v2 offset:0
	s_waitcnt lgkmcnt(0)
	v_mul_f32_e32 v34, v34, v94
	v_mul_f32_e32 v50, v50, v94
	v_mul_f32_e32 v35, v35, v95
	v_mul_f32_e32 v51, v51, v95
	v_mul_f32_e32 v36, v36, v96
	v_mul_f32_e32 v52, v52, v96
	v_mul_f32_e32 v37, v37, v97
	v_mul_f32_e32 v53, v53, v97
	ds_read_b128 v[94:97], v2 offset:32
	s_waitcnt lgkmcnt(0)
	v_mul_f32_e32 v38, v38, v94
	v_mul_f32_e32 v54, v54, v94
	v_mul_f32_e32 v39, v39, v95
	v_mul_f32_e32 v55, v55, v95
	v_mul_f32_e32 v40, v40, v96
	v_mul_f32_e32 v56, v56, v96
	v_mul_f32_e32 v41, v41, v97
	v_mul_f32_e32 v57, v57, v97
	ds_read_b128 v[94:97], v2 offset:64
	s_waitcnt lgkmcnt(0)
	v_mul_f32_e32 v42, v42, v94
	v_mul_f32_e32 v58, v58, v94
	v_mul_f32_e32 v43, v43, v95
	v_mul_f32_e32 v59, v59, v95
	v_mul_f32_e32 v44, v44, v96
	v_mul_f32_e32 v60, v60, v96
	v_mul_f32_e32 v45, v45, v97
	v_mul_f32_e32 v61, v61, v97
	ds_read_b128 v[94:97], v2 offset:96
	s_waitcnt lgkmcnt(0)
	v_mul_f32_e32 v46, v46, v94
	v_mul_f32_e32 v62, v62, v94
	v_mul_f32_e32 v47, v47, v95
	v_mul_f32_e32 v63, v63, v95
	v_mul_f32_e32 v48, v48, v96
	v_mul_f32_e32 v64, v64, v96
	v_mul_f32_e32 v49, v49, v97
	v_mul_f32_e32 v65, v65, v97

.Lmy_nors_31:
	s_waitcnt lgkmcnt(0)
	v_add_u32_e32 v2, 0x2000, v237
	v_mfma_f32_32x32x16_bf16 v[82:97], v[218:221], v[4:7], v[66:81]
	v_exp_f32_e32 v142, v142
	v_exp_f32_e32 v143, v143
	v_exp_f32_e32 v144, v144
	v_add_f32_e32 v27, v142, v143
	v_exp_f32_e32 v145, v145
	ds_read_b64_tr_b16 v[114:115], v2 offset:49152
	ds_read_b64_tr_b16 v[116:117], v2 offset:49664
	ds_read_b64_tr_b16 v[118:119], v2 offset:50176
	ds_read_b64_tr_b16 v[120:121], v2 offset:50688
	v_mfma_f32_32x32x16_bf16 v[98:113], v[214:217], v[4:7], v[66:81]
	v_exp_f32_e32 v146, v146
	v_add_f32_e32 v27, v27, v144
	v_exp_f32_e32 v147, v147
	v_add_f32_e32 v27, v27, v145
	v_exp_f32_e32 v148, v148
	ds_read_b64_tr_b16 v[122:123], v2 offset:51200
	ds_read_b64_tr_b16 v[124:125], v2 offset:51712
	ds_read_b64_tr_b16 v[126:127], v2 offset:52224
	ds_read_b64_tr_b16 v[128:129], v2 offset:52736
	v_mfma_f32_32x32x16_bf16 v[82:97], v[210:213], v[8:11], v[82:97]
	v_add_f32_e32 v27, v27, v146
	v_exp_f32_e32 v149, v149
	v_add_f32_e32 v27, v27, v147
	v_add_f32_e32 v27, v27, v148
	v_add_f32_e32 v27, v27, v149
	ds_read_b64_tr_b16 v[240:241], v2 offset:53248
	ds_read_b64_tr_b16 v[242:243], v2 offset:53760
	ds_read_b64_tr_b16 v[244:245], v2 offset:54272
	ds_read_b64_tr_b16 v[246:247], v2 offset:54784
	v_mfma_f32_32x32x16_bf16 v[98:113], v[206:209], v[8:11], v[98:113]
	v_cvt_pk_bf16_f32 v142, v142, v143
	v_cvt_pk_bf16_f32 v143, v144, v145
	v_cvt_pk_bf16_f32 v144, v146, v147
	v_cvt_pk_bf16_f32 v145, v148, v149
	ds_read_b64_tr_b16 v[248:249], v2 offset:55296
	ds_read_b64_tr_b16 v[250:251], v2 offset:55808
	ds_read_b64_tr_b16 v[20:21], v2 offset:56320
	ds_read_b64_tr_b16 v[22:23], v2 offset:56832
	v_mfma_f32_32x32x16_bf16 v[82:97], v[202:205], v[12:15], v[82:97]
	v_exp_f32_e32 v150, v150
	v_exp_f32_e32 v151, v151
	v_exp_f32_e32 v152, v152
	v_add_f32_e32 v27, v27, v150
	v_exp_f32_e32 v153, v153
	v_mfma_f32_32x32x16_bf16 v[98:113], v[198:201], v[12:15], v[98:113]
	v_add_f32_e32 v27, v27, v151
	v_exp_f32_e32 v154, v154
	v_add_f32_e32 v27, v27, v152
	v_exp_f32_e32 v155, v155
	v_add_f32_e32 v27, v27, v153
	v_mfma_f32_32x32x16_bf16 v[82:97], v[194:197], v[130:133], v[82:97]
	v_exp_f32_e32 v156, v156
	v_add_f32_e32 v27, v27, v154
	v_exp_f32_e32 v157, v157
	v_add_f32_e32 v27, v27, v155
	v_add_f32_e32 v27, v27, v156
	v_mfma_f32_32x32x16_bf16 v[98:113], v[190:193], v[130:133], v[98:113]
	v_add_f32_e32 v27, v27, v157
	v_cvt_pk_bf16_f32 v150, v150, v151
	v_cvt_pk_bf16_f32 v151, v152, v153
	v_cvt_pk_bf16_f32 v152, v154, v155
	v_cvt_pk_bf16_f32 v153, v156, v157
	v_mfma_f32_32x32x16_bf16 v[82:97], v[186:189], v[134:137], v[82:97]
	v_exp_f32_e32 v158, v158
	v_exp_f32_e32 v159, v159
	v_exp_f32_e32 v160, v160
	v_add_f32_e32 v27, v27, v158
	v_exp_f32_e32 v161, v161
	v_mfma_f32_32x32x16_bf16 v[98:113], v[182:185], v[134:137], v[98:113]
	v_add_f32_e32 v27, v27, v159
	v_exp_f32_e32 v162, v162
	v_add_f32_e32 v27, v27, v160
	v_exp_f32_e32 v163, v163
	v_add_f32_e32 v27, v27, v161
	v_mfma_f32_32x32x16_bf16 v[82:97], v[178:181], v[138:141], v[82:97]
	v_exp_f32_e32 v164, v164
	v_add_f32_e32 v27, v27, v162
	v_exp_f32_e32 v165, v165
	v_add_f32_e32 v27, v27, v163
	v_add_f32_e32 v27, v27, v164
	v_mfma_f32_32x32x16_bf16 v[98:113], v[174:177], v[138:141], v[98:113]
	v_add_f32_e32 v27, v27, v165
	v_cvt_pk_bf16_f32 v158, v158, v159
	v_cvt_pk_bf16_f32 v159, v160, v161
	v_cvt_pk_bf16_f32 v160, v162, v163
	v_cvt_pk_bf16_f32 v161, v164, v165
	s_waitcnt vmcnt(3)
	s_barrier
	s_waitcnt lgkmcnt(0)
	v_add_u32_e32 v2, 0x9000, v238
	v_mfma_f32_32x32x16_bf16 v[34:49], v[142:145], v[114:117], v[34:49]
	s_add_u32 m0, s57, 0x0
	v_exp_f32_e32 v166, v166
	v_exp_f32_e32 v167, v167
	global_load_lds_dwordx4 v[28:29], off
	v_lshl_add_u64 v[28:29], v[28:29], 0, s[30:31]
	v_exp_f32_e32 v168, v168
	v_add_f32_e32 v27, v27, v166
	v_exp_f32_e32 v169, v169
	ds_read_b128 v[218:221], v2
	ds_read_b128 v[214:217], v2 offset:512
	ds_read_b128 v[210:213], v2 offset:2048
	v_mfma_f32_32x32x16_bf16 v[50:65], v[142:145], v[240:243], v[50:65]
	s_add_u32 m0, s40, 0x6000
	v_add_f32_e32 v27, v27, v167
	v_exp_f32_e32 v170, v170
	global_load_lds_dwordx4 v[24:25], off
	v_lshl_add_u64 v[24:25], v[24:25], 0, s[30:31]
	v_add_f32_e32 v27, v27, v168
	v_exp_f32_e32 v171, v171
	v_add_f32_e32 v27, v27, v169
	ds_read_b128 v[206:209], v2 offset:2560
	ds_read_b128 v[202:205], v2 offset:4096
	ds_read_b128 v[198:201], v2 offset:4608
	v_mfma_f32_32x32x16_bf16 v[34:49], v[150:153], v[118:121], v[34:49]
	v_exp_f32_e32 v172, v172
	v_add_f32_e32 v27, v27, v170
	v_exp_f32_e32 v173, v173
	v_add_f32_e32 v27, v27, v171
	v_add_f32_e32 v27, v27, v172
	ds_read_b128 v[194:197], v2 offset:6144
	ds_read_b128 v[190:193], v2 offset:6656
	ds_read_b128 v[186:189], v2 offset:8192
	v_mfma_f32_32x32x16_bf16 v[50:65], v[150:153], v[244:247], v[50:65]
	v_add_f32_e32 v27, v27, v173
	v_cvt_pk_bf16_f32 v166, v166, v167
	v_cvt_pk_bf16_f32 v167, v168, v169
	v_cvt_pk_bf16_f32 v168, v170, v171
	v_cvt_pk_bf16_f32 v169, v172, v173
	v_add_f32_e32 v236, v236, v27
	ds_read_b128 v[182:185], v2 offset:8704
	ds_read_b128 v[178:181], v2 offset:10240
	ds_read_b128 v[174:177], v2 offset:10752
	v_mfma_f32_32x32x16_bf16 v[34:49], v[158:161], v[122:125], v[34:49]
	v_max3_f32 v19, v82, v83, v84
	v_max3_f32 v26, v85, v86, v87
	v_max3_f32 v19, v19, v88, v89
	v_max3_f32 v26, v26, v90, v91
	v_mfma_f32_32x32x16_bf16 v[50:65], v[158:161], v[248:251], v[50:65]
	v_max3_f32 v19, v19, v92, v93
	v_max3_f32 v26, v26, v94, v95
	v_max3_f32 v19, v19, v96, v97
	v_max3_f32 v26, v26, v98, v99
	v_mfma_f32_32x32x16_bf16 v[34:49], v[166:169], v[126:129], v[34:49]
	v_max3_f32 v19, v19, v100, v101
	v_max3_f32 v26, v26, v102, v103
	v_max3_f32 v19, v19, v104, v105
	v_max3_f32 v26, v26, v106, v107
	v_mfma_f32_32x32x16_bf16 v[50:65], v[166:169], v[20:23], v[50:65]
	v_max3_f32 v19, v19, v108, v109
	v_max3_f32 v26, v26, v110, v111
	v_max3_f32 v19, v19, v112, v113
	v_max_f32_e32 v19, v19, v26
	v_cmp_lt_f32_e32 vcc, s41, v19
	s_cbranch_vccz .Lmy_nors_32
	s_nop 15
	s_nop 15
	v_mov_b32_e32 v26, v19
	s_nop 1
	v_permlane32_swap_b32_e32 v19, v26
	v_max_f32_e32 v19, v19, v26
	v_max_f32_e32 v19, v19, v19
	v_max_f32_e32 v150, 0, v19
	v_exp_f32_e64 v151, -v150
	v_add_f32_e32 v239, v239, v150
	v_xor_b32_e32 v66, 0x80000000, v239
	v_mov_b32_e32 v67, v66
	v_mov_b32_e32 v68, v66
	v_mov_b32_e32 v69, v66
	v_mov_b32_e32 v70, v66
	v_mov_b32_e32 v71, v66
	v_mov_b32_e32 v72, v66
	v_mov_b32_e32 v73, v66
	v_mov_b32_e32 v74, v66
	v_mov_b32_e32 v75, v66
	v_mov_b32_e32 v76, v66
	v_mov_b32_e32 v77, v66
	v_mov_b32_e32 v78, v66
	v_mov_b32_e32 v79, v66
	v_mov_b32_e32 v80, v66
	v_mov_b32_e32 v81, v66
	v_sub_f32_e32 v82, v82, v150
	v_sub_f32_e32 v83, v83, v150
	v_sub_f32_e32 v84, v84, v150
	v_sub_f32_e32 v85, v85, v150
	v_sub_f32_e32 v86, v86, v150
	v_sub_f32_e32 v87, v87, v150
	v_sub_f32_e32 v88, v88, v150
	v_sub_f32_e32 v89, v89, v150
	v_sub_f32_e32 v90, v90, v150
	v_sub_f32_e32 v91, v91, v150
	v_sub_f32_e32 v92, v92, v150
	v_sub_f32_e32 v93, v93, v150
	v_sub_f32_e32 v94, v94, v150
	v_sub_f32_e32 v95, v95, v150
	v_sub_f32_e32 v96, v96, v150
	v_sub_f32_e32 v97, v97, v150
	v_sub_f32_e32 v98, v98, v150
	v_sub_f32_e32 v99, v99, v150
	v_sub_f32_e32 v100, v100, v150
	v_sub_f32_e32 v101, v101, v150
	v_sub_f32_e32 v102, v102, v150
	v_sub_f32_e32 v103, v103, v150
	v_sub_f32_e32 v104, v104, v150
	v_sub_f32_e32 v105, v105, v150
	v_sub_f32_e32 v106, v106, v150
	v_sub_f32_e32 v107, v107, v150
	v_sub_f32_e32 v108, v108, v150
	v_sub_f32_e32 v109, v109, v150
	v_sub_f32_e32 v110, v110, v150
	v_sub_f32_e32 v111, v111, v150
	v_sub_f32_e32 v112, v112, v150
	v_sub_f32_e32 v113, v113, v150
	v_mul_f32_e32 v236, v236, v151
	s_mov_b64 s[96:97], exec
	s_and_b64 exec, exec, s[8:9]
	ds_write_b32 v235, v151
	s_mov_b64 exec, s[96:97]
	v_lshl_add_u32 v2, v228, 4, s47
	ds_read_b128 v[154:157], v2 offset:0
	s_waitcnt lgkmcnt(0)
	v_mul_f32_e32 v34, v34, v154
	v_mul_f32_e32 v50, v50, v154
	v_mul_f32_e32 v35, v35, v155
	v_mul_f32_e32 v51, v51, v155
	v_mul_f32_e32 v36, v36, v156
	v_mul_f32_e32 v52, v52, v156
	v_mul_f32_e32 v37, v37, v157
	v_mul_f32_e32 v53, v53, v157
	ds_read_b128 v[154:157], v2 offset:32
	s_waitcnt lgkmcnt(0)
	v_mul_f32_e32 v38, v38, v154
	v_mul_f32_e32 v54, v54, v154
	v_mul_f32_e32 v39, v39, v155
	v_mul_f32_e32 v55, v55, v155
	v_mul_f32_e32 v40, v40, v156
	v_mul_f32_e32 v56, v56, v156
	v_mul_f32_e32 v41, v41, v157
	v_mul_f32_e32 v57, v57, v157
	ds_read_b128 v[154:157], v2 offset:64
	s_waitcnt lgkmcnt(0)
	v_mul_f32_e32 v42, v42, v154
	v_mul_f32_e32 v58, v58, v154
	v_mul_f32_e32 v43, v43, v155
	v_mul_f32_e32 v59, v59, v155
	v_mul_f32_e32 v44, v44, v156
	v_mul_f32_e32 v60, v60, v156
	v_mul_f32_e32 v45, v45, v157
	v_mul_f32_e32 v61, v61, v157
	ds_read_b128 v[154:157], v2 offset:96
	s_waitcnt lgkmcnt(0)
	v_mul_f32_e32 v46, v46, v154
	v_mul_f32_e32 v62, v62, v154
	v_mul_f32_e32 v47, v47, v155
	v_mul_f32_e32 v63, v63, v155
	v_mul_f32_e32 v48, v48, v156
	v_mul_f32_e32 v64, v64, v156
	v_mul_f32_e32 v49, v49, v157
	v_mul_f32_e32 v65, v65, v157

.Lmy_nors_33:
	s_waitcnt lgkmcnt(0)
	v_add_u32_e32 v2, 0x6000, v237
	v_mfma_f32_32x32x16_bf16 v[82:97], v[218:221], v[4:7], v[66:81]
	v_exp_f32_e32 v142, v142
	v_exp_f32_e32 v143, v143
	v_exp_f32_e32 v144, v144
	v_add_f32_e32 v27, v142, v143
	v_exp_f32_e32 v145, v145
	ds_read_b64_tr_b16 v[114:115], v2 offset:49152
	ds_read_b64_tr_b16 v[116:117], v2 offset:49664
	ds_read_b64_tr_b16 v[118:119], v2 offset:50176
	ds_read_b64_tr_b16 v[120:121], v2 offset:50688
	v_mfma_f32_32x32x16_bf16 v[98:113], v[214:217], v[4:7], v[66:81]
	v_exp_f32_e32 v146, v146
	v_add_f32_e32 v27, v27, v144
	v_exp_f32_e32 v147, v147
	v_add_f32_e32 v27, v27, v145
	v_exp_f32_e32 v148, v148
	ds_read_b64_tr_b16 v[122:123], v2 offset:51200
	ds_read_b64_tr_b16 v[124:125], v2 offset:51712
	ds_read_b64_tr_b16 v[126:127], v2 offset:52224
	ds_read_b64_tr_b16 v[128:129], v2 offset:52736
	v_mfma_f32_32x32x16_bf16 v[82:97], v[210:213], v[8:11], v[82:97]
	v_add_f32_e32 v27, v27, v146
	v_exp_f32_e32 v149, v149
	v_add_f32_e32 v27, v27, v147
	v_add_f32_e32 v27, v27, v148
	v_add_f32_e32 v27, v27, v149
	ds_read_b64_tr_b16 v[240:241], v2 offset:53248
	ds_read_b64_tr_b16 v[242:243], v2 offset:53760
	ds_read_b64_tr_b16 v[244:245], v2 offset:54272
	ds_read_b64_tr_b16 v[246:247], v2 offset:54784
	v_mfma_f32_32x32x16_bf16 v[98:113], v[206:209], v[8:11], v[98:113]
	v_cvt_pk_bf16_f32 v142, v142, v143
	v_cvt_pk_bf16_f32 v143, v144, v145
	v_cvt_pk_bf16_f32 v144, v146, v147
	v_cvt_pk_bf16_f32 v145, v148, v149
	ds_read_b64_tr_b16 v[248:249], v2 offset:55296
	ds_read_b64_tr_b16 v[250:251], v2 offset:55808
	ds_read_b64_tr_b16 v[20:21], v2 offset:56320
	ds_read_b64_tr_b16 v[22:23], v2 offset:56832
	v_mfma_f32_32x32x16_bf16 v[82:97], v[202:205], v[12:15], v[82:97]
	v_exp_f32_e32 v150, v150
	v_exp_f32_e32 v151, v151
	v_exp_f32_e32 v152, v152
	v_add_f32_e32 v27, v27, v150
	v_exp_f32_e32 v153, v153
	v_mfma_f32_32x32x16_bf16 v[98:113], v[198:201], v[12:15], v[98:113]
	v_add_f32_e32 v27, v27, v151
	v_exp_f32_e32 v154, v154
	v_add_f32_e32 v27, v27, v152
	v_exp_f32_e32 v155, v155
	v_add_f32_e32 v27, v27, v153
	v_mfma_f32_32x32x16_bf16 v[82:97], v[194:197], v[130:133], v[82:97]
	v_exp_f32_e32 v156, v156
	v_add_f32_e32 v27, v27, v154
	v_exp_f32_e32 v157, v157
	v_add_f32_e32 v27, v27, v155
	v_add_f32_e32 v27, v27, v156
	v_mfma_f32_32x32x16_bf16 v[98:113], v[190:193], v[130:133], v[98:113]
	v_add_f32_e32 v27, v27, v157
	v_cvt_pk_bf16_f32 v150, v150, v151
	v_cvt_pk_bf16_f32 v151, v152, v153
	v_cvt_pk_bf16_f32 v152, v154, v155
	v_cvt_pk_bf16_f32 v153, v156, v157
	v_mfma_f32_32x32x16_bf16 v[82:97], v[186:189], v[134:137], v[82:97]
	v_exp_f32_e32 v158, v158
	v_exp_f32_e32 v159, v159
	v_exp_f32_e32 v160, v160
	v_add_f32_e32 v27, v27, v158
	v_exp_f32_e32 v161, v161
	v_mfma_f32_32x32x16_bf16 v[98:113], v[182:185], v[134:137], v[98:113]
	v_add_f32_e32 v27, v27, v159
	v_exp_f32_e32 v162, v162
	v_add_f32_e32 v27, v27, v160
	v_exp_f32_e32 v163, v163
	v_add_f32_e32 v27, v27, v161
	v_mfma_f32_32x32x16_bf16 v[82:97], v[178:181], v[138:141], v[82:97]
	v_exp_f32_e32 v164, v164
	v_add_f32_e32 v27, v27, v162
	v_exp_f32_e32 v165, v165
	v_add_f32_e32 v27, v27, v163
	v_add_f32_e32 v27, v27, v164
	v_mfma_f32_32x32x16_bf16 v[98:113], v[174:177], v[138:141], v[98:113]
	v_add_f32_e32 v27, v27, v165
	v_cvt_pk_bf16_f32 v158, v158, v159
	v_cvt_pk_bf16_f32 v159, v160, v161
	v_cvt_pk_bf16_f32 v160, v162, v163
	v_cvt_pk_bf16_f32 v161, v164, v165
	s_waitcnt vmcnt(3)
	s_barrier
	s_waitcnt lgkmcnt(0)
	v_add_u32_e32 v2, 0x3000, v238
	v_mfma_f32_32x32x16_bf16 v[34:49], v[142:145], v[114:117], v[34:49]
	s_add_u32 m0, s57, 0x4000
	v_exp_f32_e32 v166, v166
	v_exp_f32_e32 v167, v167
	global_load_lds_dwordx4 v[28:29], off
	v_lshl_add_u64 v[28:29], v[28:29], 0, s[30:31]
	v_exp_f32_e32 v168, v168
	v_add_f32_e32 v27, v27, v166
	v_exp_f32_e32 v169, v169
	ds_read_b128 v[218:221], v2
	ds_read_b128 v[214:217], v2 offset:512
	ds_read_b128 v[210:213], v2 offset:2048
	v_mfma_f32_32x32x16_bf16 v[50:65], v[142:145], v[240:243], v[50:65]
	s_cmp_eq_u32 s79, 1
	s_cbranch_scc1 .Lmy_gl_34
	s_add_u32 m0, s40, 0x0
	s_nop 0
	global_load_lds_dwordx4 v[24:25], off
	v_lshl_add_u64 v[24:25], v[24:25], 0, s[30:31]

.Lmy_B_loop:
	s_waitcnt lgkmcnt(0)
	v_mov_b32_e32 v2, v237
	v_mfma_f32_32x32x16_bf16 v[142:157], v[218:221], v[4:7], v[66:81]
	v_exp_f32_e32 v82, v82
	v_exp_f32_e32 v83, v83
	v_exp_f32_e32 v84, v84
	v_add_f32_e32 v27, v82, v83
	v_exp_f32_e32 v85, v85
	ds_read_b64_tr_b16 v[114:115], v2 offset:49152
	ds_read_b64_tr_b16 v[116:117], v2 offset:49664
	ds_read_b64_tr_b16 v[118:119], v2 offset:50176
	ds_read_b64_tr_b16 v[120:121], v2 offset:50688
	v_mfma_f32_32x32x16_bf16 v[158:173], v[214:217], v[4:7], v[66:81]
	v_exp_f32_e32 v86, v86
	v_add_f32_e32 v27, v27, v84
	v_exp_f32_e32 v87, v87
	v_add_f32_e32 v27, v27, v85
	v_exp_f32_e32 v88, v88
	ds_read_b64_tr_b16 v[122:123], v2 offset:51200
	ds_read_b64_tr_b16 v[124:125], v2 offset:51712
	ds_read_b64_tr_b16 v[126:127], v2 offset:52224
	ds_read_b64_tr_b16 v[128:129], v2 offset:52736
	v_mfma_f32_32x32x16_bf16 v[142:157], v[210:213], v[8:11], v[142:157]
	v_add_f32_e32 v27, v27, v86
	v_exp_f32_e32 v89, v89
	v_add_f32_e32 v27, v27, v87
	v_add_f32_e32 v27, v27, v88
	v_add_f32_e32 v27, v27, v89
	ds_read_b64_tr_b16 v[240:241], v2 offset:53248
	ds_read_b64_tr_b16 v[242:243], v2 offset:53760
	ds_read_b64_tr_b16 v[244:245], v2 offset:54272
	ds_read_b64_tr_b16 v[246:247], v2 offset:54784
	v_mfma_f32_32x32x16_bf16 v[158:173], v[206:209], v[8:11], v[158:173]
	v_cvt_pk_bf16_f32 v82, v82, v83
	v_cvt_pk_bf16_f32 v83, v84, v85
	v_cvt_pk_bf16_f32 v84, v86, v87
	v_cvt_pk_bf16_f32 v85, v88, v89
	ds_read_b64_tr_b16 v[248:249], v2 offset:55296
	ds_read_b64_tr_b16 v[250:251], v2 offset:55808
	ds_read_b64_tr_b16 v[20:21], v2 offset:56320
	ds_read_b64_tr_b16 v[22:23], v2 offset:56832
	v_mfma_f32_32x32x16_bf16 v[142:157], v[202:205], v[12:15], v[142:157]
	v_exp_f32_e32 v90, v90
	v_exp_f32_e32 v91, v91
	v_exp_f32_e32 v92, v92
	v_add_f32_e32 v27, v27, v90
	v_exp_f32_e32 v93, v93
	v_mfma_f32_32x32x16_bf16 v[158:173], v[198:201], v[12:15], v[158:173]
	v_add_f32_e32 v27, v27, v91
	v_exp_f32_e32 v94, v94
	v_add_f32_e32 v27, v27, v92
	v_exp_f32_e32 v95, v95
	v_add_f32_e32 v27, v27, v93
	v_mfma_f32_32x32x16_bf16 v[142:157], v[194:197], v[130:133], v[142:157]
	v_exp_f32_e32 v96, v96
	v_add_f32_e32 v27, v27, v94
	v_exp_f32_e32 v97, v97
	v_add_f32_e32 v27, v27, v95
	v_add_f32_e32 v27, v27, v96
	v_mfma_f32_32x32x16_bf16 v[158:173], v[190:193], v[130:133], v[158:173]
	v_add_f32_e32 v27, v27, v97
	v_cvt_pk_bf16_f32 v90, v90, v91
	v_cvt_pk_bf16_f32 v91, v92, v93
	v_cvt_pk_bf16_f32 v92, v94, v95
	v_cvt_pk_bf16_f32 v93, v96, v97
	v_mfma_f32_32x32x16_bf16 v[142:157], v[186:189], v[134:137], v[142:157]
	v_exp_f32_e32 v98, v98
	v_exp_f32_e32 v99, v99
	v_exp_f32_e32 v100, v100
	v_add_f32_e32 v27, v27, v98
	v_exp_f32_e32 v101, v101
	v_mfma_f32_32x32x16_bf16 v[158:173], v[182:185], v[134:137], v[158:173]
	v_add_f32_e32 v27, v27, v99
	v_exp_f32_e32 v102, v102
	v_add_f32_e32 v27, v27, v100
	v_exp_f32_e32 v103, v103
	v_add_f32_e32 v27, v27, v101
	v_mfma_f32_32x32x16_bf16 v[142:157], v[178:181], v[138:141], v[142:157]
	v_exp_f32_e32 v104, v104
	v_add_f32_e32 v27, v27, v102
	v_exp_f32_e32 v105, v105
	v_add_f32_e32 v27, v27, v103
	v_add_f32_e32 v27, v27, v104
	v_mfma_f32_32x32x16_bf16 v[158:173], v[174:177], v[138:141], v[158:173]
	v_add_f32_e32 v27, v27, v105
	v_cvt_pk_bf16_f32 v98, v98, v99
	v_cvt_pk_bf16_f32 v99, v100, v101
	v_cvt_pk_bf16_f32 v100, v102, v103
	v_cvt_pk_bf16_f32 v101, v104, v105
	s_waitcnt vmcnt(3)
	s_barrier
	s_waitcnt lgkmcnt(0)
	v_add_u32_e32 v2, 0x6000, v238
	v_mfma_f32_32x32x16_bf16 v[34:49], v[82:85], v[114:117], v[34:49]
	s_add_u32 m0, s57, 0x6000
	v_exp_f32_e32 v106, v106
	v_exp_f32_e32 v107, v107
	global_load_lds_dwordx4 v[28:29], off
	v_lshl_add_u64 v[28:29], v[28:29], 0, s[30:31]
	v_exp_f32_e32 v108, v108
	v_add_f32_e32 v27, v27, v106
	v_exp_f32_e32 v109, v109
	ds_read_b128 v[218:221], v2
	ds_read_b128 v[214:217], v2 offset:512
	ds_read_b128 v[210:213], v2 offset:2048
	v_mfma_f32_32x32x16_bf16 v[50:65], v[82:85], v[240:243], v[50:65]
	s_add_u32 m0, s40, 0x3000
	v_add_f32_e32 v27, v27, v107
	v_exp_f32_e32 v110, v110
	global_load_lds_dwordx4 v[24:25], off
	v_lshl_add_u64 v[24:25], v[24:25], 0, s[30:31]
	v_add_f32_e32 v27, v27, v108
	v_exp_f32_e32 v111, v111
	v_add_f32_e32 v27, v27, v109
	ds_read_b128 v[206:209], v2 offset:2560
	ds_read_b128 v[202:205], v2 offset:4096
	ds_read_b128 v[198:201], v2 offset:4608
	v_mfma_f32_32x32x16_bf16 v[34:49], v[90:93], v[118:121], v[34:49]
	v_exp_f32_e32 v112, v112
	v_add_f32_e32 v27, v27, v110
	v_exp_f32_e32 v113, v113
	v_add_f32_e32 v27, v27, v111
	v_add_f32_e32 v27, v27, v112
	ds_read_b128 v[194:197], v2 offset:6144
	ds_read_b128 v[190:193], v2 offset:6656
	ds_read_b128 v[186:189], v2 offset:8192
	v_mfma_f32_32x32x16_bf16 v[50:65], v[90:93], v[244:247], v[50:65]
	v_add_f32_e32 v27, v27, v113
	v_cvt_pk_bf16_f32 v106, v106, v107
	v_cvt_pk_bf16_f32 v107, v108, v109
	v_cvt_pk_bf16_f32 v108, v110, v111
	v_cvt_pk_bf16_f32 v109, v112, v113
	v_add_f32_e32 v236, v236, v27
	ds_read_b128 v[182:185], v2 offset:8704
	ds_read_b128 v[178:181], v2 offset:10240
	ds_read_b128 v[174:177], v2 offset:10752
	v_mfma_f32_32x32x16_bf16 v[34:49], v[98:101], v[122:125], v[34:49]
	v_max3_f32 v19, v142, v143, v144
	v_max3_f32 v26, v145, v146, v147
	v_max3_f32 v19, v19, v148, v149
	v_max3_f32 v26, v26, v150, v151
	v_mfma_f32_32x32x16_bf16 v[50:65], v[98:101], v[248:251], v[50:65]
	v_max3_f32 v19, v19, v152, v153
	v_max3_f32 v26, v26, v154, v155
	v_max3_f32 v19, v19, v156, v157
	v_max3_f32 v26, v26, v158, v159
	v_mfma_f32_32x32x16_bf16 v[34:49], v[106:109], v[126:129], v[34:49]
	v_max3_f32 v19, v19, v160, v161
	v_max3_f32 v26, v26, v162, v163
	v_max3_f32 v19, v19, v164, v165
	v_max3_f32 v26, v26, v166, v167
	v_mfma_f32_32x32x16_bf16 v[50:65], v[106:109], v[20:23], v[50:65]
	v_max3_f32 v19, v19, v168, v169
	v_max3_f32 v26, v26, v170, v171
	v_max3_f32 v19, v19, v172, v173
	v_max_f32_e32 v19, v19, v26
	v_cmp_lt_f32_e32 vcc, s41, v19
	s_cbranch_vccz .Lmy_nors_36
	s_nop 15
	s_nop 15
	v_mov_b32_e32 v26, v19
	s_nop 1
	v_permlane32_swap_b32_e32 v19, v26
	v_max_f32_e32 v19, v19, v26
	v_max_f32_e32 v19, v19, v19
	v_max_f32_e32 v90, 0, v19
	v_exp_f32_e64 v91, -v90
	v_add_f32_e32 v239, v239, v90
	v_xor_b32_e32 v66, 0x80000000, v239
	v_mov_b32_e32 v67, v66
	v_mov_b32_e32 v68, v66
	v_mov_b32_e32 v69, v66
	v_mov_b32_e32 v70, v66
	v_mov_b32_e32 v71, v66
	v_mov_b32_e32 v72, v66
	v_mov_b32_e32 v73, v66
	v_mov_b32_e32 v74, v66
	v_mov_b32_e32 v75, v66
	v_mov_b32_e32 v76, v66
	v_mov_b32_e32 v77, v66
	v_mov_b32_e32 v78, v66
	v_mov_b32_e32 v79, v66
	v_mov_b32_e32 v80, v66
	v_mov_b32_e32 v81, v66
	v_sub_f32_e32 v142, v142, v90
	v_sub_f32_e32 v143, v143, v90
	v_sub_f32_e32 v144, v144, v90
	v_sub_f32_e32 v145, v145, v90
	v_sub_f32_e32 v146, v146, v90
	v_sub_f32_e32 v147, v147, v90
	v_sub_f32_e32 v148, v148, v90
	v_sub_f32_e32 v149, v149, v90
	v_sub_f32_e32 v150, v150, v90
	v_sub_f32_e32 v151, v151, v90
	v_sub_f32_e32 v152, v152, v90
	v_sub_f32_e32 v153, v153, v90
	v_sub_f32_e32 v154, v154, v90
	v_sub_f32_e32 v155, v155, v90
	v_sub_f32_e32 v156, v156, v90
	v_sub_f32_e32 v157, v157, v90
	v_sub_f32_e32 v158, v158, v90
	v_sub_f32_e32 v159, v159, v90
	v_sub_f32_e32 v160, v160, v90
	v_sub_f32_e32 v161, v161, v90
	v_sub_f32_e32 v162, v162, v90
	v_sub_f32_e32 v163, v163, v90
	v_sub_f32_e32 v164, v164, v90
	v_sub_f32_e32 v165, v165, v90
	v_sub_f32_e32 v166, v166, v90
	v_sub_f32_e32 v167, v167, v90
	v_sub_f32_e32 v168, v168, v90
	v_sub_f32_e32 v169, v169, v90
	v_sub_f32_e32 v170, v170, v90
	v_sub_f32_e32 v171, v171, v90
	v_sub_f32_e32 v172, v172, v90
	v_sub_f32_e32 v173, v173, v90
	v_mul_f32_e32 v236, v236, v91
	s_mov_b64 s[96:97], exec
	s_and_b64 exec, exec, s[8:9]
	ds_write_b32 v235, v91
	s_mov_b64 exec, s[96:97]
	v_lshl_add_u32 v2, v228, 4, s47
	ds_read_b128 v[94:97], v2 offset:0
	s_waitcnt lgkmcnt(0)
	v_mul_f32_e32 v34, v34, v94
	v_mul_f32_e32 v50, v50, v94
	v_mul_f32_e32 v35, v35, v95
	v_mul_f32_e32 v51, v51, v95
	v_mul_f32_e32 v36, v36, v96
	v_mul_f32_e32 v52, v52, v96
	v_mul_f32_e32 v37, v37, v97
	v_mul_f32_e32 v53, v53, v97
	ds_read_b128 v[94:97], v2 offset:32
	s_waitcnt lgkmcnt(0)
	v_mul_f32_e32 v38, v38, v94
	v_mul_f32_e32 v54, v54, v94
	v_mul_f32_e32 v39, v39, v95
	v_mul_f32_e32 v55, v55, v95
	v_mul_f32_e32 v40, v40, v96
	v_mul_f32_e32 v56, v56, v96
	v_mul_f32_e32 v41, v41, v97
	v_mul_f32_e32 v57, v57, v97
	ds_read_b128 v[94:97], v2 offset:64
	s_waitcnt lgkmcnt(0)
	v_mul_f32_e32 v42, v42, v94
	v_mul_f32_e32 v58, v58, v94
	v_mul_f32_e32 v43, v43, v95
	v_mul_f32_e32 v59, v59, v95
	v_mul_f32_e32 v44, v44, v96
	v_mul_f32_e32 v60, v60, v96
	v_mul_f32_e32 v45, v45, v97
	v_mul_f32_e32 v61, v61, v97
	ds_read_b128 v[94:97], v2 offset:96
	s_waitcnt lgkmcnt(0)
	v_mul_f32_e32 v46, v46, v94
	v_mul_f32_e32 v62, v62, v94
	v_mul_f32_e32 v47, v47, v95
	v_mul_f32_e32 v63, v63, v95
	v_mul_f32_e32 v48, v48, v96
	v_mul_f32_e32 v64, v64, v96
	v_mul_f32_e32 v49, v49, v97
	v_mul_f32_e32 v65, v65, v97
